# s_sleep 80 (2us) pacing at the top of each P0 weight-transposer iteration, on top of h1pf
# speedup vs baseline: 1.0119x; 1.0053x over previous
; __device__ __forceinline__ void p0_prologue(const Ptrs& P, LAS unsigned char* lds, int vcu, int G, int tid) {
;     ...
;         for (int it = gw; it < NITEMS; it += NGW) {
;             const int nit = it + NGW; const bool has_n = nit < NITEMS;
;             f32x4 nv[8];
;             const TItem nxt = t_decode(P, has_n ? nit : it, lane); t_load(nxt, nv);
.LBB0_39:
	s_sleep 80
	s_mov_b32 s20, s50
	s_add_i32 s50, s50, s0
	s_cmp_gt_i32 s50, 0xffff
	s_cselect_b64 s[22:23], -1, 0
	s_cmp_lt_i32 s50, 0x10000
	s_cselect_b32 s53, s50, s20
	s_cmpk_gt_i32 s53, 0x3fff
	s_cbranch_scc0 .LBB0_52
	s_add_i32 s20, s53, 0xffffc000
	s_mul_hi_u32 s24, s20, 0xaaaaaaab
	s_lshr_b32 s29, s24, 9
	s_mul_i32 s24, s29, 0x300
	s_sub_i32 s28, s20, s24
	s_lshl_b32 s20, s28, 5
	s_cmpk_gt_u32 s28, 0x1ff
	s_cselect_b64 s[24:25], -1, 0
	s_mov_b64 s[26:27], -1
	s_and_b64 vcc, exec, s[24:25]
	s_cbranch_vccz .LBB0_42
	s_lshl_b32 s26, s28, 10
	s_and_b32 s26, s26, 0x1000
	s_lshl_b32 s27, s28, 4
	s_and_b32 s52, s20, 0x60
	s_and_b32 s27, s27, 0x3f80
	s_or_b32 s26, s52, s26
	s_add_i32 s26, s26, s27
	v_add_u32_e32 v68, s26, v83
	s_mov_b64 s[26:27], 0
